# q4c + relu2 epilogue canonicalising v_max folded (107 fewer VALU per unit), store-data WAR wait states padded
# baseline (speedup 1.0000x reference)
; #define PG8_STAGE(bufoff, gbase, voff) do { _Pragma("unroll") for (int _i = 0; _i < 2; ++_i) \
;         __builtin_amdgcn_global_load_lds((const unsigned*)((const char*)(gbase) + (voff)[_i]), (LAS unsigned*)(lds + (bufoff) + ldsw + _i * 8192), 16, 0, 0); } while (0)
; #define PG8_LDA(dst, b, h) do { _Pragma("unroll") for (int m = 0; m < 4; ++m) _Pragma("unroll") for (int k = 0; k < 2; ++k) dst[m][k] = *(const LAS bf16x8*)(lds + PG8_SA(b, h) + aoff + m * 2048 + k * 1024); } while (0)
; #define PG8_LDB(dst, b, h) do { _Pragma("unroll") for (int n = 0; n < 2; ++n) _Pragma("unroll") for (int k = 0; k < 2; ++k) dst[n][k] = *(const LAS bf16x8*)(lds + PG8_SB(b, h) + boff + n * 2048 + k * 1024); } while (0)
; #define PG8_MMA(ai, bj, At, Bt) do { __builtin_amdgcn_s_setprio(1); _Pragma("unroll") for (int m = 0; m < 4; ++m) _Pragma("unroll") for (int n = 0; n < 2; ++n) _Pragma("unroll") for (int k = 0; k < 2; ++k) \
;         acc[ai][bj][m][n] = __builtin_amdgcn_mfma_f32_16x16x32_bf16(Bt[n][k], At[m][k], acc[ai][bj][m][n], 0, 0, 0); __builtin_amdgcn_s_setprio(0); } while (0)
; template <class Epi, class Sched>
; __device__ __forceinline__ void gemm_phase(LAS unsigned char* lds, const Gemm g, const Sched& S, const Epi& E) {
;     ...
;             const bool last = (t == nt - 2);
;             const char* a1 = cA + (size_t)(t + 1) * kstep;
;             const char* a2 = last ? nA : cA + (size_t)(t + 2) * kstep; const char* b2 = last ? nB : cB + (size_t)(t + 2) * kstep;
;             const char* a3 = a2 + kstep; const char* b3 = b2 + kstep;
;             PG8_LDB(B0, 0, 0); PG8_SCHED; PG8_LDA(At, 0, 0); PG8_STAGE(PG8_SA(1, 1), a1 + hstep, voffA);
;             PG8_WAIT_L(8); PG8_BAR; PG8_WAIT_L(0); PG8_MMA(0, 0, At, B0); PG8_BAR; PG8_SCHED;
;             PG8_LDB(B1, 0, 1); PG8_STAGE(PG8_SB(0, 0), b2, voffB);
;             PG8_BAR; PG8_WAIT_L(0); PG8_MMA(0, 1, At, B1); PG8_BAR;
;             PG8_LDA(At, 0, 1); PG8_STAGE(PG8_SA(0, 0), a2, voffA);
;             PG8_BAR; PG8_WAIT_L(0); PG8_MMA(1, 0, At, B0); PG8_BAR; PG8_SCHED;
;             PG8_STAGE(PG8_SB(0, 1), b2 + hstep, voffB);
;             PG8_WAIT_V(6); PG8_BAR; PG8_MMA(1, 1, At, B1); PG8_BAR;
;             PG8_LDB(B0, 1, 0); PG8_SCHED; PG8_LDA(At, 1, 0); PG8_STAGE(PG8_SA(0, 1), a2 + hstep, voffA);
;             PG8_WAIT_L(8); PG8_BAR; PG8_WAIT_L(0); PG8_MMA(0, 0, At, B0); PG8_BAR; PG8_SCHED;
.LBB0_73:
	s_add_u32 s38, s46, 0xfff80080
	s_addc_u32 s39, s47, -1
	s_cmp_eq_u32 s73, 28
	s_cselect_b32 s51, s29, s39
	s_cselect_b32 s50, s69, s38
	s_cselect_b32 s49, s27, s72
	s_cselect_b32 s48, s70, s71
	v_lshl_add_u64 v[140:141], s[46:47], 0, v[138:139]
	s_add_i32 m0, s9, 0xc000
	s_nop 0
	global_load_lds_dwordx4 v[140:141], off
	v_lshl_add_u64 v[140:141], s[46:47], 0, v[136:137]
	s_add_i32 m0, s9, 0xe000
	s_nop 0
	global_load_lds_dwordx4 v[140:141], off
	s_add_i32 s74, 0, 0x10000
	v_add_u32_e32 v140, s74, v143
	ds_read_b128 v[146:149], v140
	ds_read_b128 v[150:153], v140 offset:1024
	ds_read_b128 v[154:157], v140 offset:2048
	ds_read_b128 v[160:163], v140 offset:3072
	ds_read_b128 v[164:167], v145
	ds_read_b128 v[168:171], v145 offset:1024
	ds_read_b128 v[172:175], v145 offset:2048
	ds_read_b128 v[176:179], v145 offset:3072
	ds_read_b128 v[180:183], v145 offset:4096
	ds_read_b128 v[184:187], v145 offset:5120
	ds_read_b128 v[188:191], v145 offset:6144
	ds_read_b128 v[192:195], v145 offset:7168
	s_add_i32 s75, 0, 0x14000
	v_add_u32_e32 v140, s75, v143
	ds_read_b128 v[196:199], v140
	ds_read_b128 v[200:203], v140 offset:1024
	ds_read_b128 v[204:207], v140 offset:2048
	ds_read_b128 v[210:213], v140 offset:3072
	s_waitcnt lgkmcnt(4)
	s_barrier
	s_waitcnt lgkmcnt(0)
	s_setprio 1
	v_mfma_f32_16x16x32_bf16 v[126:129], v[146:149], v[164:167], v[126:129]
	v_mfma_f32_16x16x32_bf16 v[122:125], v[154:157], v[164:167], v[122:125]
	v_mfma_f32_16x16x32_bf16 v[110:113], v[146:149], v[172:175], v[110:113]
	v_mfma_f32_16x16x32_bf16 v[106:109], v[154:157], v[172:175], v[106:109]
	v_mfma_f32_16x16x32_bf16 v[94:97], v[146:149], v[180:183], v[94:97]
	v_mfma_f32_16x16x32_bf16 v[90:93], v[154:157], v[180:183], v[90:93]
	v_mfma_f32_16x16x32_bf16 v[78:81], v[146:149], v[188:191], v[78:81]
	v_mfma_f32_16x16x32_bf16 v[74:77], v[154:157], v[188:191], v[74:77]
	v_mfma_f32_16x16x32_bf16 v[126:129], v[150:153], v[168:171], v[126:129]
	v_mfma_f32_16x16x32_bf16 v[122:125], v[160:163], v[168:171], v[122:125]
	v_mfma_f32_16x16x32_bf16 v[110:113], v[150:153], v[176:179], v[110:113]
	v_mfma_f32_16x16x32_bf16 v[106:109], v[160:163], v[176:179], v[106:109]
	v_mfma_f32_16x16x32_bf16 v[94:97], v[150:153], v[184:187], v[94:97]
	v_mfma_f32_16x16x32_bf16 v[90:93], v[160:163], v[184:187], v[90:93]
	v_mfma_f32_16x16x32_bf16 v[78:81], v[150:153], v[192:195], v[78:81]
	v_mfma_f32_16x16x32_bf16 v[74:77], v[160:163], v[192:195], v[74:77]
	v_mfma_f32_16x16x32_bf16 v[118:121], v[196:199], v[164:167], v[118:121]
	v_mfma_f32_16x16x32_bf16 v[114:117], v[204:207], v[164:167], v[114:117]
	v_mfma_f32_16x16x32_bf16 v[102:105], v[196:199], v[172:175], v[102:105]
	v_mfma_f32_16x16x32_bf16 v[98:101], v[204:207], v[172:175], v[98:101]
	v_mfma_f32_16x16x32_bf16 v[86:89], v[196:199], v[180:183], v[86:89]
	v_mfma_f32_16x16x32_bf16 v[82:85], v[204:207], v[180:183], v[82:85]
	v_mfma_f32_16x16x32_bf16 v[70:73], v[196:199], v[188:191], v[70:73]
	v_mfma_f32_16x16x32_bf16 v[66:69], v[204:207], v[188:191], v[66:69]
	v_mfma_f32_16x16x32_bf16 v[118:121], v[200:203], v[168:171], v[118:121]
	v_mfma_f32_16x16x32_bf16 v[114:117], v[210:213], v[168:171], v[114:117]
	v_mfma_f32_16x16x32_bf16 v[102:105], v[200:203], v[176:179], v[102:105]
	v_mfma_f32_16x16x32_bf16 v[98:101], v[210:213], v[176:179], v[98:101]
	v_mfma_f32_16x16x32_bf16 v[86:89], v[200:203], v[184:187], v[86:89]
	v_mfma_f32_16x16x32_bf16 v[82:85], v[210:213], v[184:187], v[82:85]
	v_mfma_f32_16x16x32_bf16 v[70:73], v[200:203], v[192:195], v[70:73]
	v_mfma_f32_16x16x32_bf16 v[66:69], v[210:213], v[192:195], v[66:69]
	s_setprio 0
	s_barrier
	s_add_i32 s38, s74, s56
	v_lshl_add_u64 v[140:141], s[48:49], 0, v[0:1]
	s_mov_b32 m0, s38
	v_lshl_add_u64 v[214:215], s[48:49], 0, v[130:131]
	global_load_lds_dwordx4 v[140:141], off
	s_add_i32 m0, s38, 0x2000
	s_nop 0
	global_load_lds_dwordx4 v[214:215], off
	s_mov_b32 m0, s9
	v_lshl_add_u64 v[216:217], s[50:51], 0, v[134:135]
	global_load_lds_dwordx4 v[216:217], off
	v_lshl_add_u64 v[224:225], s[50:51], 0, v[132:133]
	s_mov_b32 m0, s60
	s_nop 0
	global_load_lds_dwordx4 v[224:225], off
	ds_read_b128 v[164:167], v145 offset:16384
	ds_read_b128 v[168:171], v145 offset:17408
	ds_read_b128 v[172:175], v145 offset:18432
	ds_read_b128 v[176:179], v145 offset:19456
	ds_read_b128 v[180:183], v145 offset:20480
	ds_read_b128 v[184:187], v145 offset:21504
	ds_read_b128 v[188:191], v145 offset:22528
	ds_read_b128 v[192:195], v145 offset:23552
	s_waitcnt vmcnt(4)
	s_waitcnt lgkmcnt(0)
	s_barrier
	s_setprio 1
	v_mfma_f32_16x16x32_bf16 v[62:65], v[146:149], v[164:167], v[62:65]
	v_mfma_f32_16x16x32_bf16 v[58:61], v[154:157], v[164:167], v[58:61]
	v_mfma_f32_16x16x32_bf16 v[46:49], v[146:149], v[172:175], v[46:49]
	v_mfma_f32_16x16x32_bf16 v[42:45], v[154:157], v[172:175], v[42:45]
	v_mfma_f32_16x16x32_bf16 v[30:33], v[146:149], v[180:183], v[30:33]
	v_mfma_f32_16x16x32_bf16 v[26:29], v[154:157], v[180:183], v[26:29]
	v_mfma_f32_16x16x32_bf16 v[14:17], v[146:149], v[188:191], v[14:17]
	v_mfma_f32_16x16x32_bf16 v[10:13], v[154:157], v[188:191], v[10:13]
	v_mfma_f32_16x16x32_bf16 v[62:65], v[150:153], v[168:171], v[62:65]
	v_mfma_f32_16x16x32_bf16 v[58:61], v[160:163], v[168:171], v[58:61]
	v_mfma_f32_16x16x32_bf16 v[46:49], v[150:153], v[176:179], v[46:49]
	v_mfma_f32_16x16x32_bf16 v[42:45], v[160:163], v[176:179], v[42:45]
	v_mfma_f32_16x16x32_bf16 v[30:33], v[150:153], v[184:187], v[30:33]
	v_mfma_f32_16x16x32_bf16 v[26:29], v[160:163], v[184:187], v[26:29]
	v_mfma_f32_16x16x32_bf16 v[14:17], v[150:153], v[192:195], v[14:17]
	v_mfma_f32_16x16x32_bf16 v[10:13], v[160:163], v[192:195], v[10:13]
	v_mfma_f32_16x16x32_bf16 v[54:57], v[196:199], v[164:167], v[54:57]
	v_mfma_f32_16x16x32_bf16 v[50:53], v[204:207], v[164:167], v[50:53]
	v_mfma_f32_16x16x32_bf16 v[38:41], v[196:199], v[172:175], v[38:41]
	v_mfma_f32_16x16x32_bf16 v[34:37], v[204:207], v[172:175], v[34:37]
	v_mfma_f32_16x16x32_bf16 v[22:25], v[196:199], v[180:183], v[22:25]
	v_mfma_f32_16x16x32_bf16 v[18:21], v[204:207], v[180:183], v[18:21]
	v_mfma_f32_16x16x32_bf16 v[6:9], v[196:199], v[188:191], v[6:9]
	v_mfma_f32_16x16x32_bf16 v[2:5], v[204:207], v[188:191], v[2:5]
	v_mfma_f32_16x16x32_bf16 v[54:57], v[200:203], v[168:171], v[54:57]
	v_mfma_f32_16x16x32_bf16 v[50:53], v[210:213], v[168:171], v[50:53]
	v_mfma_f32_16x16x32_bf16 v[38:41], v[200:203], v[176:179], v[38:41]
	v_mfma_f32_16x16x32_bf16 v[34:37], v[210:213], v[176:179], v[34:37]
	v_mfma_f32_16x16x32_bf16 v[22:25], v[200:203], v[184:187], v[22:25]
	v_mfma_f32_16x16x32_bf16 v[18:21], v[210:213], v[184:187], v[18:21]
	v_mfma_f32_16x16x32_bf16 v[6:9], v[200:203], v[192:195], v[6:9]
	v_mfma_f32_16x16x32_bf16 v[2:5], v[210:213], v[192:195], v[2:5]
	s_setprio 0
	s_barrier
; #define PG8_STAGE(bufoff, gbase, voff) do { _Pragma("unroll") for (int _i = 0; _i < 2; ++_i) \
;         __builtin_amdgcn_global_load_lds((const unsigned*)((const char*)(gbase) + (voff)[_i]), (LAS unsigned*)(lds + (bufoff) + ldsw + _i * 8192), 16, 0, 0); } while (0)
; #define PG8_LDA(dst, b, h) do { _Pragma("unroll") for (int m = 0; m < 4; ++m) _Pragma("unroll") for (int k = 0; k < 2; ++k) dst[m][k] = *(const LAS bf16x8*)(lds + PG8_SA(b, h) + aoff + m * 2048 + k * 1024); } while (0)
; #define PG8_LDB(dst, b, h) do { _Pragma("unroll") for (int n = 0; n < 2; ++n) _Pragma("unroll") for (int k = 0; k < 2; ++k) dst[n][k] = *(const LAS bf16x8*)(lds + PG8_SB(b, h) + boff + n * 2048 + k * 1024); } while (0)
; #define PG8_MMA(ai, bj, At, Bt) do { __builtin_amdgcn_s_setprio(1); _Pragma("unroll") for (int m = 0; m < 4; ++m) _Pragma("unroll") for (int n = 0; n < 2; ++n) _Pragma("unroll") for (int k = 0; k < 2; ++k) \
;         acc[ai][bj][m][n] = __builtin_amdgcn_mfma_f32_16x16x32_bf16(Bt[n][k], At[m][k], acc[ai][bj][m][n], 0, 0, 0); __builtin_amdgcn_s_setprio(0); } while (0)
; #define PG8_WAIT_V(n) asm volatile("s_waitcnt vmcnt(" #n ")" ::: "memory")
; #define PG8_WAIT_L(n) asm volatile("s_waitcnt lgkmcnt(" #n ")" ::: "memory")
; #define PG8_BAR __builtin_amdgcn_s_barrier()
; #define PG8_SCHED __builtin_amdgcn_sched_barrier(0)
; template <class Epi, class Sched>
; __device__ __forceinline__ void gemm_phase(LAS unsigned char* lds, const Gemm g, const Sched& S, const Epi& E) {
;     ...
;             PG8_STAGE(PG8_SB(0, 1), b2 + hstep, voffB);
;             PG8_WAIT_V(6); PG8_BAR; PG8_MMA(1, 1, At, B1); PG8_BAR;
;             PG8_LDB(B0, 1, 0); PG8_SCHED; PG8_LDA(At, 1, 0); PG8_STAGE(PG8_SA(0, 1), a2 + hstep, voffA);
;             PG8_WAIT_L(8); PG8_BAR; PG8_WAIT_L(0); PG8_MMA(0, 0, At, B0); PG8_BAR; PG8_SCHED;
;             PG8_LDB(B1, 1, 1); PG8_STAGE(PG8_SB(1, 0), b3, voffB);
;             PG8_BAR; PG8_WAIT_L(0); PG8_MMA(0, 1, At, B1); PG8_BAR;
;             PG8_LDA(At, 1, 1); PG8_STAGE(PG8_SA(1, 0), a3, voffA);
;             PG8_BAR; PG8_WAIT_L(0); PG8_MMA(1, 0, At, B0); PG8_BAR; PG8_SCHED;
	s_add_u32 s38, s48, 0x80000
	s_addc_u32 s39, s49, 0
	s_add_i32 s74, s75, s56
	v_lshl_add_u64 v[146:147], s[38:39], 0, v[0:1]
	s_mov_b32 m0, s74
	s_nop 0
	global_load_lds_dwordx4 v[146:147], off
	v_lshl_add_u64 v[146:147], s[38:39], 0, v[130:131]
	s_add_i32 m0, s74, 0x2000
	s_nop 0
	global_load_lds_dwordx4 v[146:147], off
	s_add_u32 s38, s50, 0x80000
	s_addc_u32 s39, s51, 0
	s_mov_b32 m0, s61
	v_lshl_add_u64 v[196:197], s[38:39], 0, v[134:135]
	global_load_lds_dwordx4 v[196:197], off
	v_lshl_add_u64 v[196:197], s[38:39], 0, v[132:133]
	s_mov_b32 m0, s62
	s_nop 0
	global_load_lds_dwordx4 v[196:197], off
	s_add_i32 s74, 0, 0x18000
	v_add_u32_e32 v160, s74, v143
	ds_read_b128 v[146:149], v160
	ds_read_b128 v[150:153], v160 offset:1024
	ds_read_b128 v[154:157], v160 offset:2048
	ds_read_b128 v[160:163], v160 offset:3072
	ds_read_b128 v[164:167], v145 offset:32768
	ds_read_b128 v[168:171], v145 offset:33792
	ds_read_b128 v[172:175], v145 offset:34816
	ds_read_b128 v[176:179], v145 offset:35840
	ds_read_b128 v[180:183], v145 offset:36864
	ds_read_b128 v[184:187], v145 offset:37888
	ds_read_b128 v[188:191], v145 offset:38912
	ds_read_b128 v[192:195], v145 offset:39936
	s_add_i32 s50, 0, 0x1c000
	v_add_u32_e32 v210, s50, v143
	ds_read_b128 v[196:199], v210
	ds_read_b128 v[200:203], v210 offset:1024
	ds_read_b128 v[204:207], v210 offset:2048
	ds_read_b128 v[210:213], v210 offset:3072
	s_waitcnt lgkmcnt(4)
	s_barrier
	s_waitcnt lgkmcnt(0)
	s_setprio 1
	v_mfma_f32_16x16x32_bf16 v[126:129], v[146:149], v[164:167], v[126:129]
	v_mfma_f32_16x16x32_bf16 v[122:125], v[154:157], v[164:167], v[122:125]
	v_mfma_f32_16x16x32_bf16 v[110:113], v[146:149], v[172:175], v[110:113]
	v_mfma_f32_16x16x32_bf16 v[106:109], v[154:157], v[172:175], v[106:109]
	v_mfma_f32_16x16x32_bf16 v[94:97], v[146:149], v[180:183], v[94:97]
	v_mfma_f32_16x16x32_bf16 v[90:93], v[154:157], v[180:183], v[90:93]
	v_mfma_f32_16x16x32_bf16 v[78:81], v[146:149], v[188:191], v[78:81]
	v_mfma_f32_16x16x32_bf16 v[74:77], v[154:157], v[188:191], v[74:77]
	v_mfma_f32_16x16x32_bf16 v[126:129], v[150:153], v[168:171], v[126:129]
	v_mfma_f32_16x16x32_bf16 v[122:125], v[160:163], v[168:171], v[122:125]
	v_mfma_f32_16x16x32_bf16 v[110:113], v[150:153], v[176:179], v[110:113]
	v_mfma_f32_16x16x32_bf16 v[106:109], v[160:163], v[176:179], v[106:109]
	v_mfma_f32_16x16x32_bf16 v[94:97], v[150:153], v[184:187], v[94:97]
	v_mfma_f32_16x16x32_bf16 v[90:93], v[160:163], v[184:187], v[90:93]
	v_mfma_f32_16x16x32_bf16 v[78:81], v[150:153], v[192:195], v[78:81]
	v_mfma_f32_16x16x32_bf16 v[74:77], v[160:163], v[192:195], v[74:77]
	v_mfma_f32_16x16x32_bf16 v[118:121], v[196:199], v[164:167], v[118:121]
	v_mfma_f32_16x16x32_bf16 v[114:117], v[204:207], v[164:167], v[114:117]
	v_mfma_f32_16x16x32_bf16 v[102:105], v[196:199], v[172:175], v[102:105]
	v_mfma_f32_16x16x32_bf16 v[98:101], v[204:207], v[172:175], v[98:101]
	v_mfma_f32_16x16x32_bf16 v[86:89], v[196:199], v[180:183], v[86:89]
	v_mfma_f32_16x16x32_bf16 v[82:85], v[204:207], v[180:183], v[82:85]
	v_mfma_f32_16x16x32_bf16 v[70:73], v[196:199], v[188:191], v[70:73]
	v_mfma_f32_16x16x32_bf16 v[66:69], v[204:207], v[188:191], v[66:69]
	v_mfma_f32_16x16x32_bf16 v[118:121], v[200:203], v[168:171], v[118:121]
	v_mfma_f32_16x16x32_bf16 v[114:117], v[210:213], v[168:171], v[114:117]
	v_mfma_f32_16x16x32_bf16 v[102:105], v[200:203], v[176:179], v[102:105]
	v_mfma_f32_16x16x32_bf16 v[98:101], v[210:213], v[176:179], v[98:101]
	v_mfma_f32_16x16x32_bf16 v[86:89], v[200:203], v[184:187], v[86:89]
	v_mfma_f32_16x16x32_bf16 v[82:85], v[210:213], v[184:187], v[82:85]
	v_mfma_f32_16x16x32_bf16 v[70:73], v[200:203], v[192:195], v[70:73]
	v_mfma_f32_16x16x32_bf16 v[66:69], v[210:213], v[192:195], v[66:69]
	s_setprio 0
	s_barrier
	s_add_i32 s38, s74, s56
	v_lshl_add_u64 v[140:141], v[140:141], 0, s[36:37]
	s_mov_b32 m0, s38
	s_nop 0
	global_load_lds_dwordx4 v[140:141], off
	v_lshl_add_u64 v[140:141], v[214:215], 0, s[36:37]
	s_add_i32 m0, s38, 0x2000
	s_nop 0
	global_load_lds_dwordx4 v[140:141], off
	s_mov_b32 m0, s64
	v_lshl_add_u64 v[140:141], v[216:217], 0, s[36:37]
	global_load_lds_dwordx4 v[140:141], off
	v_lshl_add_u64 v[140:141], v[224:225], 0, s[36:37]
	s_mov_b32 m0, s65
	s_nop 0
	global_load_lds_dwordx4 v[140:141], off
	ds_read_b128 v[164:167], v145 offset:49152
	ds_read_b128 v[168:171], v145 offset:50176
	ds_read_b128 v[172:175], v145 offset:51200
	ds_read_b128 v[176:179], v145 offset:52224
	ds_read_b128 v[180:183], v145 offset:53248
	ds_read_b128 v[184:187], v145 offset:54272
	ds_read_b128 v[188:191], v145 offset:55296
	ds_read_b128 v[192:195], v145 offset:56320
	s_waitcnt vmcnt(4)
	s_waitcnt lgkmcnt(0)
	s_barrier
; __device__ __forceinline__ unsigned cvt_pk_bf16(float lo, float hi) { unsigned r; asm("v_cvt_pk_bf16_f32 %0, %1, %2" : "=v"(r) : "v"(lo), "v"(hi)); return r; }
; #define PG8_STAGE(bufoff, gbase, voff) do { _Pragma("unroll") for (int _i = 0; _i < 2; ++_i) \
;         __builtin_amdgcn_global_load_lds((const unsigned*)((const char*)(gbase) + (voff)[_i]), (LAS unsigned*)(lds + (bufoff) + ldsw + _i * 8192), 16, 0, 0); } while (0)
; #define PG8_LDA(dst, b, h) do { _Pragma("unroll") for (int m = 0; m < 4; ++m) _Pragma("unroll") for (int k = 0; k < 2; ++k) dst[m][k] = *(const LAS bf16x8*)(lds + PG8_SA(b, h) + aoff + m * 2048 + k * 1024); } while (0)
; #define PG8_WAIT_V(n) asm volatile("s_waitcnt vmcnt(" #n ")" ::: "memory")
; #define PG8_BAR __builtin_amdgcn_s_barrier()
;     __device__ __forceinline__ void operator()(const f32x4 (&acc)[2][2][4][2], const Unit& u, int wr, int wc, int fr, int fq) const {
;         const int row0 = u.pm * BM + wr * 64 + fr, col0 = u.pn * BM + wc * 32 + 8 * fq;
; #pragma unroll
;         for (int ai = 0; ai < 2; ++ai)
; #pragma unroll
;             for (int m = 0; m < 4; ++m) { bf16_t* rowp = O + (size_t)(row0 + ai * HALF + m * 16) * ldc + col0;
; #pragma unroll
;                 for (int bj = 0; bj < 2; ++bj) { f32x4 v0 = acc[ai][bj][m][0], v1 = acc[ai][bj][m][1];
;                     if (ACT == 1) {
; #pragma unroll
;                         for (int j = 0; j < 4; ++j) { float a = fmaxf(v0[j], 0.f), b = fmaxf(v1[j], 0.f); v0[j] = a * a; v1[j] = b * b; } }
;                     u32x4 w; w.x = cvt_pk_bf16(v0[0], v0[1]); w.y = cvt_pk_bf16(v0[2], v0[3]); w.z = cvt_pk_bf16(v1[0], v1[1]); w.w = cvt_pk_bf16(v1[2], v1[3]);
;                     if (ACT == 1) __builtin_nontemporal_store(w, (u32x4*)(rowp + bj * HALF));
;                     else *(u32x4*)(rowp + bj * HALF) = w; } }
; template <class Epi, class Sched>
; __device__ __forceinline__ void gemm_phase(LAS unsigned char* lds, const Gemm g, const Sched& S, const Epi& E) {
;     ...
;             PG8_LDB(B1, 1, 1); PG8_STAGE(PG8_SB(1, 0), b3, voffB);
;             PG8_BAR; PG8_WAIT_L(0); PG8_MMA(0, 1, At, B1); PG8_BAR;
;             PG8_LDA(At, 1, 1); PG8_STAGE(PG8_SA(1, 0), a3, voffA);
;             PG8_BAR; PG8_WAIT_L(0); PG8_MMA(1, 0, At, B0); PG8_BAR; PG8_SCHED;
;             PG8_STAGE(PG8_SB(1, 1), b3 + hstep, voffB);
;             PG8_WAIT_V(6); PG8_BAR; PG8_MMA(1, 1, At, B1); PG8_BAR;
	s_setprio 1
	v_mfma_f32_16x16x32_bf16 v[62:65], v[146:149], v[164:167], v[62:65]
	v_mfma_f32_16x16x32_bf16 v[58:61], v[154:157], v[164:167], v[58:61]
	v_mfma_f32_16x16x32_bf16 v[46:49], v[146:149], v[172:175], v[46:49]
	v_mfma_f32_16x16x32_bf16 v[42:45], v[154:157], v[172:175], v[42:45]
	v_mfma_f32_16x16x32_bf16 v[30:33], v[146:149], v[180:183], v[30:33]
	v_mfma_f32_16x16x32_bf16 v[26:29], v[154:157], v[180:183], v[26:29]
	v_mfma_f32_16x16x32_bf16 v[14:17], v[146:149], v[188:191], v[14:17]
	v_mfma_f32_16x16x32_bf16 v[10:13], v[154:157], v[188:191], v[10:13]
	v_mfma_f32_16x16x32_bf16 v[62:65], v[150:153], v[168:171], v[62:65]
	v_mfma_f32_16x16x32_bf16 v[58:61], v[160:163], v[168:171], v[58:61]
	v_mfma_f32_16x16x32_bf16 v[46:49], v[150:153], v[176:179], v[46:49]
	v_mfma_f32_16x16x32_bf16 v[42:45], v[160:163], v[176:179], v[42:45]
	v_mfma_f32_16x16x32_bf16 v[30:33], v[150:153], v[184:187], v[30:33]
	v_mfma_f32_16x16x32_bf16 v[26:29], v[160:163], v[184:187], v[26:29]
	v_mfma_f32_16x16x32_bf16 v[14:17], v[150:153], v[192:195], v[14:17]
	v_mfma_f32_16x16x32_bf16 v[10:13], v[160:163], v[192:195], v[10:13]
	s_add_u32 s38, s48, 0x80080
	s_addc_u32 s39, s49, 0
	s_add_i32 s48, s50, s56
	v_lshl_add_u64 v[140:141], s[38:39], 0, v[0:1]
	s_mov_b32 m0, s48
	s_nop 0
	global_load_lds_dwordx4 v[140:141], off
	v_lshl_add_u64 v[140:141], s[38:39], 0, v[130:131]
	s_add_i32 m0, s48, 0x2000
	s_nop 0
	global_load_lds_dwordx4 v[140:141], off
	v_mfma_f32_16x16x32_bf16 v[54:57], v[196:199], v[164:167], v[54:57]
	v_mfma_f32_16x16x32_bf16 v[50:53], v[204:207], v[164:167], v[50:53]
	v_mfma_f32_16x16x32_bf16 v[38:41], v[196:199], v[172:175], v[38:41]
	v_mfma_f32_16x16x32_bf16 v[34:37], v[204:207], v[172:175], v[34:37]
	v_mfma_f32_16x16x32_bf16 v[22:25], v[196:199], v[180:183], v[22:25]
	v_mfma_f32_16x16x32_bf16 v[18:21], v[204:207], v[180:183], v[18:21]
	v_mfma_f32_16x16x32_bf16 v[6:9], v[196:199], v[188:191], v[6:9]
	v_mfma_f32_16x16x32_bf16 v[2:5], v[204:207], v[188:191], v[2:5]
	v_mfma_f32_16x16x32_bf16 v[54:57], v[200:203], v[168:171], v[54:57]
	v_mfma_f32_16x16x32_bf16 v[50:53], v[210:213], v[168:171], v[50:53]
	v_mfma_f32_16x16x32_bf16 v[38:41], v[200:203], v[176:179], v[38:41]
	v_mfma_f32_16x16x32_bf16 v[34:37], v[210:213], v[176:179], v[34:37]
	v_mfma_f32_16x16x32_bf16 v[22:25], v[200:203], v[184:187], v[22:25]
	v_mfma_f32_16x16x32_bf16 v[18:21], v[210:213], v[184:187], v[18:21]
	v_mfma_f32_16x16x32_bf16 v[6:9], v[200:203], v[192:195], v[6:9]
	v_mfma_f32_16x16x32_bf16 v[2:5], v[210:213], v[192:195], v[2:5]
	s_setprio 0
	s_add_i32 s73, s73, 2
	s_add_u32 s71, s71, 0x100
	s_addc_u32 s72, s72, 0
	s_add_u32 s46, s46, 0x100
	s_addc_u32 s47, s47, 0
	s_cmp_gt_u32 s73, 29
	s_barrier
	s_cbranch_scc0 .LBB0_73
	v_lshl_add_u32 v146, s8, 8, v142
	v_ashrrev_i32_e32 v147, 31, v146
	v_max_f32_e32 v122, 0, v122
	v_lshl_or_b32 v140, s68, 8, v144
	v_lshlrev_b64 v[148:149], 14, v[146:147]
	v_mul_f32_e32 v147, v122, v122
	v_max_f32_e32 v123, 0, v123
	v_max_f32_e32 v124, 0, v124
	v_ashrrev_i32_e32 v141, 31, v140
	v_max_f32_e32 v122, 0, v127
	v_mul_f32_e32 v127, v123, v123
	v_max_f32_e32 v123, v128, v128
	v_mul_f32_e32 v128, v124, v124
	v_lshl_add_u64 v[148:149], s[24:25], 0, v[148:149]
	v_lshlrev_b64 v[150:151], 1, v[140:141]
	v_max_f32_e32 v126, 0, v126
	v_mul_f32_e32 v122, v122, v122
	v_max_f32_e32 v123, 0, v123
	v_max_f32_e32 v124, 0, v129
	v_max_f32_e32 v125, 0, v125
	v_lshl_add_u64 v[140:141], v[148:149], 0, v[150:151]
	v_mul_f32_e32 v126, v126, v126
	v_mul_f32_e32 v123, v123, v123
	v_mul_f32_e32 v124, v124, v124
	v_mul_f32_e32 v125, v125, v125
	v_cvt_pk_bf16_f32 v122, v126, v122
	v_max_f32_e32 v114, 0, v114
	v_cvt_pk_bf16_f32 v123, v123, v124
	v_cvt_pk_bf16_f32 v124, v147, v127
	v_cvt_pk_bf16_f32 v125, v128, v125
	global_store_dwordx4 v[140:141], v[122:125], off nt
	v_max_f32_e32 v115, 0, v115
	v_max_f32_e32 v116, 0, v116
	v_mul_f32_e32 v122, v114, v114
	v_max_f32_e32 v114, 0, v119
	v_mul_f32_e32 v119, v115, v115
	v_max_f32_e32 v115, v120, v120
	v_mul_f32_e32 v120, v116, v116
	v_max_f32_e32 v118, 0, v118
	v_mul_f32_e32 v114, v114, v114
	v_max_f32_e32 v115, 0, v115
	v_max_f32_e32 v116, 0, v121
	v_max_f32_e32 v117, 0, v117
	v_mul_f32_e32 v118, v118, v118
	v_mul_f32_e32 v115, v115, v115
	v_mul_f32_e32 v116, v116, v116
	v_mul_f32_e32 v117, v117, v117
	v_cvt_pk_bf16_f32 v114, v118, v114
	v_cvt_pk_bf16_f32 v115, v115, v116
	v_cvt_pk_bf16_f32 v116, v122, v119
	v_cvt_pk_bf16_f32 v117, v120, v117
	global_store_dwordx4 v[140:141], v[114:117], off offset:256 nt
	s_nop 1
	v_max_f32_e32 v106, 0, v106
	v_or_b32_e32 v114, 16, v146
	v_ashrrev_i32_e32 v115, 31, v114
	v_mul_f32_e32 v116, v106, v106
	v_max_f32_e32 v107, 0, v107
	v_max_f32_e32 v108, 0, v108
	v_lshlrev_b64 v[114:115], 14, v[114:115]
	v_max_f32_e32 v106, 0, v111
	v_mul_f32_e32 v111, v107, v107
	v_max_f32_e32 v107, v112, v112
	v_mul_f32_e32 v112, v108, v108
	v_lshl_add_u64 v[114:115], s[24:25], 0, v[114:115]
	v_max_f32_e32 v110, 0, v110
	v_mul_f32_e32 v106, v106, v106
	v_max_f32_e32 v107, 0, v107
	v_max_f32_e32 v108, 0, v113
	v_max_f32_e32 v109, 0, v109
	v_lshl_add_u64 v[114:115], v[114:115], 0, v[150:151]
	v_mul_f32_e32 v110, v110, v110
	v_mul_f32_e32 v107, v107, v107
	v_mul_f32_e32 v108, v108, v108
	v_mul_f32_e32 v109, v109, v109
	v_cvt_pk_bf16_f32 v106, v110, v106
	v_max_f32_e32 v98, 0, v98
	v_cvt_pk_bf16_f32 v107, v107, v108
	v_cvt_pk_bf16_f32 v108, v116, v111
	v_cvt_pk_bf16_f32 v109, v112, v109
	global_store_dwordx4 v[114:115], v[106:109], off nt
	v_max_f32_e32 v99, 0, v99
	v_max_f32_e32 v100, 0, v100
	v_mul_f32_e32 v106, v98, v98
	v_max_f32_e32 v98, 0, v103
	v_mul_f32_e32 v103, v99, v99
	v_max_f32_e32 v99, v104, v104
; __device__ __forceinline__ unsigned cvt_pk_bf16(float lo, float hi) { unsigned r; asm("v_cvt_pk_bf16_f32 %0, %1, %2" : "=v"(r) : "v"(lo), "v"(hi)); return r; }
;     __device__ __forceinline__ void operator()(const f32x4 (&acc)[2][2][4][2], const Unit& u, int wr, int wc, int fr, int fq) const {
;         const int row0 = u.pm * BM + wr * 64 + fr, col0 = u.pn * BM + wc * 32 + 8 * fq;
; #pragma unroll
;         for (int ai = 0; ai < 2; ++ai)
; #pragma unroll
;             for (int m = 0; m < 4; ++m) { bf16_t* rowp = O + (size_t)(row0 + ai * HALF + m * 16) * ldc + col0;
; #pragma unroll
;                 for (int bj = 0; bj < 2; ++bj) { f32x4 v0 = acc[ai][bj][m][0], v1 = acc[ai][bj][m][1];
;                     if (ACT == 1) {
; #pragma unroll
;                         for (int j = 0; j < 4; ++j) { float a = fmaxf(v0[j], 0.f), b = fmaxf(v1[j], 0.f); v0[j] = a * a; v1[j] = b * b; } }
;                     u32x4 w; w.x = cvt_pk_bf16(v0[0], v0[1]); w.y = cvt_pk_bf16(v0[2], v0[3]); w.z = cvt_pk_bf16(v1[0], v1[1]); w.w = cvt_pk_bf16(v1[2], v1[3]);
;                     if (ACT == 1) __builtin_nontemporal_store(w, (u32x4*)(rowp + bj * HALF));
;                     else *(u32x4*)(rowp + bj * HALF) = w; } }
	v_mul_f32_e32 v104, v100, v100
	v_max_f32_e32 v102, 0, v102
	v_mul_f32_e32 v98, v98, v98
	v_max_f32_e32 v99, 0, v99
	v_max_f32_e32 v100, 0, v105
	v_max_f32_e32 v101, 0, v101
	v_mul_f32_e32 v102, v102, v102
	v_mul_f32_e32 v99, v99, v99
	v_mul_f32_e32 v100, v100, v100
	v_mul_f32_e32 v101, v101, v101
	v_cvt_pk_bf16_f32 v98, v102, v98
	v_cvt_pk_bf16_f32 v99, v99, v100
	v_cvt_pk_bf16_f32 v100, v106, v103
	v_cvt_pk_bf16_f32 v101, v104, v101
	global_store_dwordx4 v[114:115], v[98:101], off offset:256 nt
	s_nop 1
	v_max_f32_e32 v90, 0, v90
	v_or_b32_e32 v98, 32, v146
	v_ashrrev_i32_e32 v99, 31, v98
	v_mul_f32_e32 v100, v90, v90
	v_max_f32_e32 v91, 0, v91
	v_max_f32_e32 v92, 0, v92
	v_lshlrev_b64 v[98:99], 14, v[98:99]
	v_max_f32_e32 v90, 0, v95
	v_mul_f32_e32 v95, v91, v91
	v_max_f32_e32 v91, v96, v96
	v_mul_f32_e32 v96, v92, v92
	v_lshl_add_u64 v[98:99], s[24:25], 0, v[98:99]
	v_max_f32_e32 v94, 0, v94
	v_mul_f32_e32 v90, v90, v90
	v_max_f32_e32 v91, 0, v91
	v_max_f32_e32 v92, 0, v97
	v_max_f32_e32 v93, 0, v93
	v_lshl_add_u64 v[98:99], v[98:99], 0, v[150:151]
	v_mul_f32_e32 v94, v94, v94
	v_mul_f32_e32 v91, v91, v91
	v_mul_f32_e32 v92, v92, v92
	v_mul_f32_e32 v93, v93, v93
	v_cvt_pk_bf16_f32 v90, v94, v90
	v_max_f32_e32 v82, 0, v82
	v_cvt_pk_bf16_f32 v91, v91, v92
	v_cvt_pk_bf16_f32 v92, v100, v95
	v_cvt_pk_bf16_f32 v93, v96, v93
	global_store_dwordx4 v[98:99], v[90:93], off nt
	v_max_f32_e32 v83, 0, v83
	v_max_f32_e32 v84, 0, v84
	v_mul_f32_e32 v90, v82, v82
	v_max_f32_e32 v82, 0, v87
	v_mul_f32_e32 v87, v83, v83
	v_max_f32_e32 v83, v88, v88
	v_mul_f32_e32 v88, v84, v84
	v_max_f32_e32 v86, 0, v86
	v_mul_f32_e32 v82, v82, v82
	v_max_f32_e32 v83, 0, v83
	v_max_f32_e32 v84, 0, v89
	v_max_f32_e32 v85, 0, v85
	v_mul_f32_e32 v86, v86, v86
	v_mul_f32_e32 v83, v83, v83
	v_mul_f32_e32 v84, v84, v84
	v_mul_f32_e32 v85, v85, v85
	v_cvt_pk_bf16_f32 v82, v86, v82
	v_cvt_pk_bf16_f32 v83, v83, v84
	v_cvt_pk_bf16_f32 v84, v90, v87
	v_cvt_pk_bf16_f32 v85, v88, v85
	global_store_dwordx4 v[98:99], v[82:85], off offset:256 nt
	s_nop 1
	v_max_f32_e32 v74, 0, v74
	v_or_b32_e32 v82, 48, v146
	v_ashrrev_i32_e32 v83, 31, v82
	v_mul_f32_e32 v84, v74, v74
	v_max_f32_e32 v75, 0, v75
	v_max_f32_e32 v76, 0, v76
	v_lshlrev_b64 v[82:83], 14, v[82:83]
	v_max_f32_e32 v74, 0, v79
	v_mul_f32_e32 v79, v75, v75
	v_max_f32_e32 v75, v80, v80
	v_mul_f32_e32 v80, v76, v76
	v_lshl_add_u64 v[82:83], s[24:25], 0, v[82:83]
	v_max_f32_e32 v78, 0, v78
	v_mul_f32_e32 v74, v74, v74
	v_max_f32_e32 v75, 0, v75
	v_max_f32_e32 v76, 0, v81
	v_max_f32_e32 v77, 0, v77
	v_lshl_add_u64 v[82:83], v[82:83], 0, v[150:151]
	v_mul_f32_e32 v78, v78, v78
	v_mul_f32_e32 v75, v75, v75
	v_mul_f32_e32 v76, v76, v76
	v_mul_f32_e32 v77, v77, v77
	v_cvt_pk_bf16_f32 v74, v78, v74
	v_max_f32_e32 v66, 0, v66
	v_max_f32_e32 v67, 0, v67
	v_max_f32_e32 v68, 0, v68
	v_cvt_pk_bf16_f32 v75, v75, v76
	v_cvt_pk_bf16_f32 v76, v84, v79
	v_cvt_pk_bf16_f32 v77, v80, v77
	global_store_dwordx4 v[82:83], v[74:77], off nt
	s_nop 1
	v_mul_f32_e32 v74, v66, v66
	v_max_f32_e32 v66, v71, v71
	v_mul_f32_e32 v71, v67, v67
	v_max_f32_e32 v67, v72, v72
	v_mul_f32_e32 v72, v68, v68
	v_max_f32_e32 v67, 0, v67
	v_max_f32_e32 v68, 0, v73
	v_max_f32_e32 v66, 0, v66
	v_mul_f32_e32 v67, v67, v67
	v_max_f32_e32 v69, 0, v69
	v_mul_f32_e32 v68, v68, v68
	v_max_f32_e32 v70, 0, v70
	v_mul_f32_e32 v66, v66, v66
	v_mul_f32_e32 v69, v69, v69
	v_cvt_pk_bf16_f32 v67, v67, v68
	v_cvt_pk_bf16_f32 v68, v74, v71
	v_max_f32_e32 v58, 0, v58
	v_mul_f32_e32 v70, v70, v70
	v_cvt_pk_bf16_f32 v66, v70, v66
	v_cvt_pk_bf16_f32 v69, v72, v69
	global_store_dwordx4 v[82:83], v[66:69], off offset:256 nt
	s_nop 1
	v_max_f32_e32 v59, 0, v59
	v_mul_f32_e32 v68, v58, v58
	v_max_f32_e32 v60, 0, v60
	v_max_f32_e32 v62, 0, v62
	v_max_f32_e32 v58, 0, v63
	v_mul_f32_e32 v63, v59, v59
	v_max_f32_e32 v59, v64, v64
	v_mul_f32_e32 v64, v60, v60
	v_mul_f32_e32 v62, v62, v62
	v_mul_f32_e32 v58, v58, v58
	v_max_f32_e32 v59, 0, v59
	v_max_f32_e32 v60, 0, v65
	s_mov_b32 s8, 0x200000
	v_mul_f32_e32 v59, v59, v59
	v_max_f32_e32 v61, 0, v61
	v_mul_f32_e32 v60, v60, v60
	v_cvt_pk_bf16_f32 v58, v62, v58
	v_add_co_u32_e32 v62, vcc, s8, v140
	v_mul_f32_e32 v61, v61, v61
	v_cvt_pk_bf16_f32 v59, v59, v60
	v_cvt_pk_bf16_f32 v60, v68, v63
	v_addc_co_u32_e32 v63, vcc, 0, v141, vcc
	v_max_f32_e32 v50, 0, v50
	v_max_f32_e32 v51, 0, v51
	v_max_f32_e32 v52, 0, v52
	v_cvt_pk_bf16_f32 v61, v64, v61
	global_store_dwordx4 v[62:63], v[58:61], off nt
	s_nop 1
	s_mov_b64 s[38:39], 0x200000
	v_mul_f32_e32 v58, v50, v50
	v_max_f32_e32 v50, v55, v55
	v_mul_f32_e32 v55, v51, v51
	v_max_f32_e32 v51, v56, v56
	v_mul_f32_e32 v56, v52, v52
	v_max_f32_e32 v51, 0, v51
	v_max_f32_e32 v52, 0, v57
	v_max_f32_e32 v50, 0, v50
	v_mul_f32_e32 v51, v51, v51
	v_max_f32_e32 v53, 0, v53
	v_mul_f32_e32 v52, v52, v52
	v_lshl_add_u64 v[66:67], v[140:141], 0, s[38:39]
	v_max_f32_e32 v54, 0, v54
	v_mul_f32_e32 v50, v50, v50
	v_mul_f32_e32 v53, v53, v53
	v_cvt_pk_bf16_f32 v51, v51, v52
	v_cvt_pk_bf16_f32 v52, v58, v55
; __device__ __forceinline__ unsigned cvt_pk_bf16(float lo, float hi) { unsigned r; asm("v_cvt_pk_bf16_f32 %0, %1, %2" : "=v"(r) : "v"(lo), "v"(hi)); return r; }
; #define PG8_WAIT_V(n) asm volatile("s_waitcnt vmcnt(" #n ")" ::: "memory")
; #define PG8_BAR __builtin_amdgcn_s_barrier()
;     __device__ __forceinline__ void operator()(const f32x4 (&acc)[2][2][4][2], const Unit& u, int wr, int wc, int fr, int fq) const {
;         const int row0 = u.pm * BM + wr * 64 + fr, col0 = u.pn * BM + wc * 32 + 8 * fq;
; #pragma unroll
;         for (int ai = 0; ai < 2; ++ai)
; #pragma unroll
;             for (int m = 0; m < 4; ++m) { bf16_t* rowp = O + (size_t)(row0 + ai * HALF + m * 16) * ldc + col0;
; #pragma unroll
;                 for (int bj = 0; bj < 2; ++bj) { f32x4 v0 = acc[ai][bj][m][0], v1 = acc[ai][bj][m][1];
;                     if (ACT == 1) {
; #pragma unroll
;                         for (int j = 0; j < 4; ++j) { float a = fmaxf(v0[j], 0.f), b = fmaxf(v1[j], 0.f); v0[j] = a * a; v1[j] = b * b; } }
;                     u32x4 w; w.x = cvt_pk_bf16(v0[0], v0[1]); w.y = cvt_pk_bf16(v0[2], v0[3]); w.z = cvt_pk_bf16(v1[0], v1[1]); w.w = cvt_pk_bf16(v1[2], v1[3]);
;                     if (ACT == 1) __builtin_nontemporal_store(w, (u32x4*)(rowp + bj * HALF));
;                     else *(u32x4*)(rowp + bj * HALF) = w; } }
; template <class Epi, class Sched>
; __device__ __forceinline__ void gemm_phase(LAS unsigned char* lds, const Gemm g, const Sched& S, const Epi& E) {
;     ...
;         cur = nxt; cA = nA; cB = nB; ++ui;
;     }
;     PG8_WAIT_V(0);
;     if (wr == 0) PG8_BAR;
;     PG8_BAR;
	v_max_f32_e32 v42, 0, v42
	v_mul_f32_e32 v54, v54, v54
	v_cvt_pk_bf16_f32 v50, v54, v50
	v_cvt_pk_bf16_f32 v53, v56, v53
	global_store_dwordx4 v[66:67], v[50:53], off offset:256 nt
	s_nop 1
	v_max_f32_e32 v43, 0, v43
	v_mul_f32_e32 v52, v42, v42
	v_max_f32_e32 v44, 0, v44
	v_max_f32_e32 v46, 0, v46
	v_max_f32_e32 v42, 0, v47
	v_mul_f32_e32 v47, v43, v43
	v_max_f32_e32 v43, v48, v48
	v_mul_f32_e32 v48, v44, v44
	v_mul_f32_e32 v46, v46, v46
	v_mul_f32_e32 v42, v42, v42
	v_max_f32_e32 v43, 0, v43
	v_max_f32_e32 v44, 0, v49
	s_mov_b32 s8, 0x240000
	v_mul_f32_e32 v43, v43, v43
	v_max_f32_e32 v45, 0, v45
	v_mul_f32_e32 v44, v44, v44
	v_cvt_pk_bf16_f32 v42, v46, v42
	v_add_co_u32_e32 v46, vcc, s8, v140
	v_mul_f32_e32 v45, v45, v45
	v_cvt_pk_bf16_f32 v43, v43, v44
	v_cvt_pk_bf16_f32 v44, v52, v47
	v_addc_co_u32_e32 v47, vcc, 0, v141, vcc
	v_max_f32_e32 v34, 0, v34
	v_max_f32_e32 v35, 0, v35
	v_max_f32_e32 v36, 0, v36
	v_cvt_pk_bf16_f32 v45, v48, v45
	global_store_dwordx4 v[46:47], v[42:45], off nt
	s_nop 1
	s_mov_b64 s[38:39], 0x240000
	v_mul_f32_e32 v42, v34, v34
	v_max_f32_e32 v34, v39, v39
	v_mul_f32_e32 v39, v35, v35
	v_max_f32_e32 v35, v40, v40
	v_mul_f32_e32 v40, v36, v36
	v_max_f32_e32 v35, 0, v35
	v_max_f32_e32 v36, 0, v41
	v_max_f32_e32 v34, 0, v34
	v_mul_f32_e32 v35, v35, v35
	v_max_f32_e32 v37, 0, v37
	v_mul_f32_e32 v36, v36, v36
	v_lshl_add_u64 v[50:51], v[140:141], 0, s[38:39]
	v_max_f32_e32 v38, 0, v38
	v_mul_f32_e32 v34, v34, v34
	v_mul_f32_e32 v37, v37, v37
	v_cvt_pk_bf16_f32 v35, v35, v36
	v_cvt_pk_bf16_f32 v36, v42, v39
	v_max_f32_e32 v26, 0, v26
	v_mul_f32_e32 v38, v38, v38
	v_cvt_pk_bf16_f32 v34, v38, v34
	v_cvt_pk_bf16_f32 v37, v40, v37
	global_store_dwordx4 v[50:51], v[34:37], off offset:256 nt
	s_nop 1
	v_max_f32_e32 v27, 0, v27
	v_mul_f32_e32 v36, v26, v26
	v_max_f32_e32 v28, 0, v28
	v_max_f32_e32 v30, 0, v30
	v_max_f32_e32 v26, 0, v31
	v_mul_f32_e32 v31, v27, v27
	v_max_f32_e32 v27, v32, v32
	v_mul_f32_e32 v32, v28, v28
	v_mul_f32_e32 v30, v30, v30
	v_mul_f32_e32 v26, v26, v26
	v_max_f32_e32 v27, 0, v27
	v_max_f32_e32 v28, 0, v33
	s_mov_b32 s8, 0x280000
	v_mul_f32_e32 v27, v27, v27
	v_max_f32_e32 v29, 0, v29
	v_mul_f32_e32 v28, v28, v28
	v_cvt_pk_bf16_f32 v26, v30, v26
	v_add_co_u32_e32 v30, vcc, s8, v140
	v_mul_f32_e32 v29, v29, v29
	v_cvt_pk_bf16_f32 v27, v27, v28
	v_cvt_pk_bf16_f32 v28, v36, v31
	v_addc_co_u32_e32 v31, vcc, 0, v141, vcc
	v_max_f32_e32 v18, 0, v18
	v_max_f32_e32 v19, 0, v19
	v_max_f32_e32 v20, 0, v20
	v_cvt_pk_bf16_f32 v29, v32, v29
	global_store_dwordx4 v[30:31], v[26:29], off nt
	s_nop 1
	s_mov_b64 s[38:39], 0x280000
	v_mul_f32_e32 v26, v18, v18
	v_max_f32_e32 v18, v23, v23
	v_mul_f32_e32 v23, v19, v19
	v_max_f32_e32 v19, v24, v24
	v_mul_f32_e32 v24, v20, v20
	v_max_f32_e32 v19, 0, v19
	v_max_f32_e32 v20, 0, v25
	v_max_f32_e32 v18, 0, v18
	v_mul_f32_e32 v19, v19, v19
	v_max_f32_e32 v21, 0, v21
	v_mul_f32_e32 v20, v20, v20
	v_lshl_add_u64 v[34:35], v[140:141], 0, s[38:39]
	v_max_f32_e32 v22, 0, v22
	v_mul_f32_e32 v18, v18, v18
	v_mul_f32_e32 v21, v21, v21
	v_cvt_pk_bf16_f32 v19, v19, v20
	v_cvt_pk_bf16_f32 v20, v26, v23
	v_max_f32_e32 v10, 0, v10
	v_mul_f32_e32 v22, v22, v22
	v_cvt_pk_bf16_f32 v18, v22, v18
	v_cvt_pk_bf16_f32 v21, v24, v21
	global_store_dwordx4 v[34:35], v[18:21], off offset:256 nt
	s_nop 1
	v_max_f32_e32 v11, 0, v11
	v_mul_f32_e32 v20, v10, v10
	v_max_f32_e32 v12, 0, v12
	v_max_f32_e32 v14, 0, v14
	v_max_f32_e32 v10, 0, v15
	v_mul_f32_e32 v15, v11, v11
	v_max_f32_e32 v11, v16, v16
	v_mul_f32_e32 v16, v12, v12
	v_mul_f32_e32 v14, v14, v14
	v_mul_f32_e32 v10, v10, v10
	v_max_f32_e32 v11, 0, v11
	v_max_f32_e32 v12, 0, v17
	s_mov_b32 s8, 0x2c0000
	v_mul_f32_e32 v11, v11, v11
	v_max_f32_e32 v13, 0, v13
	v_mul_f32_e32 v12, v12, v12
	v_cvt_pk_bf16_f32 v10, v14, v10
	v_add_co_u32_e32 v14, vcc, s8, v140
	v_mul_f32_e32 v13, v13, v13
	v_cvt_pk_bf16_f32 v11, v11, v12
	v_cvt_pk_bf16_f32 v12, v20, v15
	v_addc_co_u32_e32 v15, vcc, 0, v141, vcc
	v_max_f32_e32 v2, 0, v2
	v_max_f32_e32 v3, 0, v3
	v_max_f32_e32 v4, 0, v4
	v_cvt_pk_bf16_f32 v13, v16, v13
	global_store_dwordx4 v[14:15], v[10:13], off nt
	s_nop 1
	s_mov_b64 s[38:39], 0x2c0000
	v_mul_f32_e32 v10, v2, v2
	v_max_f32_e32 v2, v7, v7
	v_mul_f32_e32 v7, v3, v3
	v_max_f32_e32 v3, v8, v8
	v_mul_f32_e32 v8, v4, v4
	v_max_f32_e32 v2, 0, v2
	v_max_f32_e32 v3, 0, v3
	v_max_f32_e32 v4, 0, v9
	v_max_f32_e32 v5, 0, v5
	v_lshl_add_u64 v[18:19], v[140:141], 0, s[38:39]
	v_max_f32_e32 v6, 0, v6
	v_mul_f32_e32 v2, v2, v2
	v_mul_f32_e32 v3, v3, v3
	v_mul_f32_e32 v4, v4, v4
	v_mul_f32_e32 v5, v5, v5
	s_and_b64 vcc, exec, s[40:41]
	s_mov_b32 s68, s26
	s_mov_b32 s8, s28
	s_mov_b64 s[46:47], s[44:45]
	s_mov_b64 s[48:49], s[42:43]
	v_mul_f32_e32 v6, v6, v6
	v_cvt_pk_bf16_f32 v2, v6, v2
	v_cvt_pk_bf16_f32 v3, v3, v4
	v_cvt_pk_bf16_f32 v4, v10, v7
	v_cvt_pk_bf16_f32 v5, v8, v5
	global_store_dwordx4 v[18:19], v[2:5], off offset:256 nt
	s_cbranch_vccz .LBB0_70
	s_waitcnt vmcnt(0)
	s_cmpk_gt_u32 s52, 0xff
	s_cbranch_scc1 .LBB0_77
	s_barrier
